# c33 + P16 second half-tile base loads widened (14 dwordx2 -> 7 dwordx4, inverse lane-group exchange after each pair's wait, counted waits recomputed)
# speedup vs baseline: 1.0234x; 1.0025x over previous
; __device__ __forceinline__ unsigned cvt_pk_bf16(float lo, float hi) { unsigned r; asm volatile("v_cvt_pk_bf16_f32 %0, %1, %2" : "=v"(r) : "v"(lo), "v"(hi)); return r; }
;     __device__ __forceinline__ void operator()(const f32x4 (&acc)[2][2][4][2], const Unit& u, int wr, int wc, int fr, int fq) const {
;     ...
;         for (int ai = 0; ai < 2; ++ai) {
;             f32x4 bv[4][2][2]; unsigned long long bw[4][2][2];
; #pragma unroll
;             for (int m = 0; m < 4; ++m) { const size_t off = (size_t)(row0 + ai * HALF + m * 16) * 1024 + col0;
; #pragma unroll
;                 for (int bj = 0; bj < 2; ++bj)
; #pragma unroll
;                     for (int n = 0; n < 2; ++n) {
;                         if (BASE_BF16) bw[m][bj][n] = __builtin_nontemporal_load((const unsigned long long*)((const bf16_t*)base + off + bj * HALF + 16 * n));
;                         else bv[m][bj][n] = __builtin_nontemporal_load((const f32x4*)((const float*)base + off + bj * HALF + 16 * n)); } }
;             asm volatile("" ::: "memory");
; #pragma unroll
;             for (int m = 0; m < 4; ++m) { const size_t off = (size_t)(row0 + ai * HALF + m * 16) * 1024 + col0;
; #pragma unroll
;                 for (int bj = 0; bj < 2; ++bj)
; #pragma unroll
;                     for (int n = 0; n < 2; ++n) {
;                         f32x4 b4;
;                         if (BASE_BF16) { const unsigned long long w = bw[m][bj][n];
;                             b4 = (f32x4){__uint_as_float((unsigned)(w & 0xffffull) << 16), __uint_as_float((unsigned)((w >> 16) & 0xffffull) << 16),
;                                          __uint_as_float((unsigned)((w >> 32) & 0xffffull) << 16), __uint_as_float((unsigned)((w >> 48) & 0xffffull) << 16)}; }
;                         else b4 = bv[m][bj][n];
;                         const f32x4 o = b4 + gv[bj][n] * acc[ai][bj][m][n];
;                         if (OUT_BF16) *(unsigned long long*)((bf16_t*)out + off + bj * HALF + 16 * n) = (unsigned long long)cvt_pk_bf16(o[0], o[1]) | ((unsigned long long)cvt_pk_bf16(o[2], o[3]) << 32);
;                         else *(f32x4*)((float*)out + off + bj * HALF + 16 * n) = o; } }
.LBB0_1483:
	v_lshl_or_b32 v128, s28, 8, v166
	v_lshl_add_u32 v160, s3, 8, v164
	v_ashrrev_i32_e32 v129, 31, v128
	v_ashrrev_i32_e32 v161, 31, v160
	v_or_b32_e32 v178, 16, v160
	v_lshl_add_u64 v[158:159], v[128:129], 1, s[8:9]
	v_lshlrev_b64 v[130:131], 11, v[160:161]
	s_lshr_b32 s3, s3, 4
	v_ashrrev_i32_e32 v179, 31, v178
	v_lshl_add_u64 v[130:131], v[158:159], 0, v[130:131]
	s_mul_i32 s16, s3, 0x1800
	v_lshlrev_b64 v[156:157], 2, v[128:129]
	v_lshlrev_b64 v[128:129], 11, v[178:179]
	v_and_b32_e32 v250, 48, v254
	v_mov_b32_e32 v251, 0
	v_lshrrev_b32_e32 v250, 1, v250
	v_lshl_add_u64 v[252:253], v[130:131], 0, v[250:251]
	global_load_dwordx4 v[170:173], v[252:253], off nt
	v_lshl_add_u64 v[252:253], v[130:131], 0, v[250:251]
	global_load_dwordx4 v[174:177], v[252:253], off offset:256 nt
	s_ashr_i32 s17, s16, 31
	v_lshl_add_u64 v[162:163], v[158:159], 0, v[128:129]
	v_lshl_add_u64 v[252:253], v[162:163], 0, v[250:251]
	global_load_dwordx4 v[180:183], v[252:253], off nt
	s_lshl_b64 s[16:17], s[16:17], 2
	s_add_u32 s16, s41, s16
	s_addc_u32 s17, s42, s17
	v_lshl_add_u64 v[128:129], s[16:17], 0, v[156:157]
	global_load_dwordx4 v[140:143], v[128:129], off
	global_load_dwordx4 v[136:139], v[128:129], off offset:64
	global_load_dwordx4 v[132:135], v[128:129], off offset:512
	s_nop 0
	global_load_dwordx4 v[128:131], v[128:129], off offset:576
	s_nop 0
	v_lshl_add_u64 v[252:253], v[162:163], 0, v[250:251]
	global_load_dwordx4 v[184:187], v[252:253], off offset:256 nt
	v_or_b32_e32 v188, 32, v160
	v_ashrrev_i32_e32 v189, 31, v188
	v_lshlrev_b64 v[192:193], 11, v[188:189]
	v_lshl_add_u64 v[192:193], v[158:159], 0, v[192:193]
	v_lshl_add_u64 v[252:253], v[192:193], 0, v[250:251]
	global_load_dwordx4 v[196:199], v[252:253], off nt
	v_or_b32_e32 v162, 48, v160
	v_ashrrev_i32_e32 v163, 31, v162
	v_lshlrev_b64 v[194:195], 11, v[162:163]
	v_lshl_add_u64 v[194:195], v[158:159], 0, v[194:195]
	global_load_dwordx2 v[200:201], v[192:193], off offset:256 nt
	s_nop 0
	global_load_dwordx2 v[192:193], v[192:193], off offset:288 nt
	s_nop 0
	v_lshl_add_u64 v[252:253], v[194:195], 0, v[250:251]
	global_load_dwordx4 v[202:205], v[252:253], off nt
	global_load_dwordx2 v[206:207], v[194:195], off offset:256 nt
	s_nop 0
	global_load_dwordx2 v[194:195], v[194:195], off offset:288 nt
	v_lshlrev_b64 v[190:191], 12, v[160:161]
	v_lshl_add_u64 v[190:191], s[50:51], 0, v[190:191]
	v_lshlrev_b64 v[178:179], 12, v[178:179]
	v_lshl_add_u64 v[190:191], v[190:191], 0, v[156:157]
	s_and_b64 vcc, exec, s[0:1]
	s_mov_b64 s[0:1], -1
	s_waitcnt vmcnt(0)
	v_permlane16_swap_b32_e32 v170, v172
	v_permlane16_swap_b32_e32 v171, v173
	v_permlane16_swap_b32_e32 v174, v176
	v_permlane16_swap_b32_e32 v175, v177
	v_permlane16_swap_b32_e32 v180, v182
	v_permlane16_swap_b32_e32 v181, v183
	v_permlane16_swap_b32_e32 v184, v186
	v_permlane16_swap_b32_e32 v185, v187
	v_permlane16_swap_b32_e32 v196, v198
	v_permlane16_swap_b32_e32 v197, v199
	v_permlane16_swap_b32_e32 v202, v204
	v_permlane16_swap_b32_e32 v203, v205
	v_permlane32_swap_b32_e32 v170, v172
	v_permlane32_swap_b32_e32 v171, v173
	v_permlane32_swap_b32_e32 v174, v176
	v_permlane32_swap_b32_e32 v175, v177
	v_permlane32_swap_b32_e32 v180, v182
	v_permlane32_swap_b32_e32 v181, v183
	v_permlane32_swap_b32_e32 v184, v186
	v_permlane32_swap_b32_e32 v185, v187
	v_permlane32_swap_b32_e32 v196, v198
	v_permlane32_swap_b32_e32 v197, v199
	v_permlane32_swap_b32_e32 v202, v204
	v_permlane32_swap_b32_e32 v203, v205
	s_nop 1
	v_alignbit_b32 v161, v171, v170, 16
	v_lshlrev_b32_e32 v208, 16, v170
	v_and_b32_e32 v209, 0xffff0000, v170
	v_and_b32_e32 v171, 0xffff0000, v171
	v_lshlrev_b32_e32 v210, 16, v172
	v_and_b32_e32 v211, 0xffff0000, v172
	v_alignbit_b32 v172, v173, v172, 16
	v_lshlrev_b32_e32 v212, 16, v174
	v_and_b32_e32 v213, 0xffff0000, v174
	v_alignbit_b32 v174, v175, v174, 16
	v_lshlrev_b32_e32 v214, 16, v176
	v_and_b32_e32 v215, 0xffff0000, v176
	v_alignbit_b32 v176, v177, v176, 16
	v_and_b32_e32 v170, 0xffff0000, v161
	v_and_b32_e32 v173, 0xffff0000, v173
	v_and_b32_e32 v175, 0xffff0000, v175
	v_and_b32_e32 v177, 0xffff0000, v177
	v_and_b32_e32 v172, 0xffff0000, v172
	v_and_b32_e32 v174, 0xffff0000, v174
	v_and_b32_e32 v176, 0xffff0000, v176
	v_alignbit_b32 v161, v181, v180, 16
	v_pk_fma_f32 v[124:125], v[124:125], v[140:141], v[208:209]
	v_pk_fma_f32 v[126:127], v[126:127], v[142:143], v[170:171]
	v_pk_fma_f32 v[112:113], v[112:113], v[132:133], v[212:213]
	v_lshlrev_b32_e32 v216, 16, v180
	v_and_b32_e32 v217, 0xffff0000, v180
	v_and_b32_e32 v181, 0xffff0000, v181
	v_and_b32_e32 v180, 0xffff0000, v161
	v_pk_fma_f32 v[120:121], v[120:121], v[136:137], v[210:211]
	v_pk_fma_f32 v[122:123], v[122:123], v[138:139], v[172:173]
	v_pk_fma_f32 v[114:115], v[114:115], v[134:135], v[174:175]
	v_pk_fma_f32 v[108:109], v[108:109], v[128:129], v[214:215]
	v_pk_fma_f32 v[110:111], v[110:111], v[130:131], v[176:177]
	global_store_dwordx4 v[190:191], v[124:127], off
	global_store_dwordx4 v[190:191], v[120:123], off offset:64
	global_store_dwordx4 v[190:191], v[112:115], off offset:512
	global_store_dwordx4 v[190:191], v[108:111], off offset:576
	s_nop 0
	v_lshl_add_u64 v[112:113], s[50:51], 0, v[178:179]
	v_pk_fma_f32 v[108:109], v[116:117], v[140:141], v[216:217]
	v_pk_fma_f32 v[110:111], v[118:119], v[142:143], v[180:181]
	v_lshl_add_u64 v[112:113], v[112:113], 0, v[156:157]
	global_store_dwordx4 v[112:113], v[108:111], off
	s_nop 1
	v_alignbit_b32 v110, v183, v182, 16
	v_lshlrev_b32_e32 v108, 16, v182
	v_and_b32_e32 v109, 0xffff0000, v182
	v_and_b32_e32 v110, 0xffff0000, v110
	v_and_b32_e32 v111, 0xffff0000, v183
	v_pk_fma_f32 v[104:105], v[104:105], v[136:137], v[108:109]
; __device__ __forceinline__ unsigned cvt_pk_bf16(float lo, float hi) { unsigned r; asm volatile("v_cvt_pk_bf16_f32 %0, %1, %2" : "=v"(r) : "v"(lo), "v"(hi)); return r; }
;     __device__ __forceinline__ void operator()(const f32x4 (&acc)[2][2][4][2], const Unit& u, int wr, int wc, int fr, int fq) const {
;     ...
;         for (int ai = 0; ai < 2; ++ai) {
;             f32x4 bv[4][2][2]; unsigned long long bw[4][2][2];
; #pragma unroll
;             for (int m = 0; m < 4; ++m) { const size_t off = (size_t)(row0 + ai * HALF + m * 16) * 1024 + col0;
; #pragma unroll
;                 for (int bj = 0; bj < 2; ++bj)
; #pragma unroll
;                     for (int n = 0; n < 2; ++n) {
;                         if (BASE_BF16) bw[m][bj][n] = __builtin_nontemporal_load((const unsigned long long*)((const bf16_t*)base + off + bj * HALF + 16 * n));
;                         else bv[m][bj][n] = __builtin_nontemporal_load((const f32x4*)((const float*)base + off + bj * HALF + 16 * n)); } }
;             asm volatile("" ::: "memory");
; #pragma unroll
;             for (int m = 0; m < 4; ++m) { const size_t off = (size_t)(row0 + ai * HALF + m * 16) * 1024 + col0;
; #pragma unroll
;                 for (int bj = 0; bj < 2; ++bj)
; #pragma unroll
;                     for (int n = 0; n < 2; ++n) {
;                         f32x4 b4;
;                         if (BASE_BF16) { const unsigned long long w = bw[m][bj][n];
;                             b4 = (f32x4){__uint_as_float((unsigned)(w & 0xffffull) << 16), __uint_as_float((unsigned)((w >> 16) & 0xffffull) << 16),
;                                          __uint_as_float((unsigned)((w >> 32) & 0xffffull) << 16), __uint_as_float((unsigned)((w >> 48) & 0xffffull) << 16)}; }
;                         else b4 = bv[m][bj][n];
;                         const f32x4 o = b4 + gv[bj][n] * acc[ai][bj][m][n];
;                         if (OUT_BF16) *(unsigned long long*)((bf16_t*)out + off + bj * HALF + 16 * n) = (unsigned long long)cvt_pk_bf16(o[0], o[1]) | ((unsigned long long)cvt_pk_bf16(o[2], o[3]) << 32);
;                         else *(f32x4*)((float*)out + off + bj * HALF + 16 * n) = o; } }
	v_pk_fma_f32 v[106:107], v[106:107], v[138:139], v[110:111]
	global_store_dwordx4 v[112:113], v[104:107], off offset:64
	s_nop 1
	v_alignbit_b32 v106, v185, v184, 16
	v_lshlrev_b32_e32 v104, 16, v184
	v_and_b32_e32 v105, 0xffff0000, v184
	v_and_b32_e32 v106, 0xffff0000, v106
	v_and_b32_e32 v107, 0xffff0000, v185
	v_pk_fma_f32 v[100:101], v[100:101], v[132:133], v[104:105]
	v_pk_fma_f32 v[102:103], v[102:103], v[134:135], v[106:107]
	global_store_dwordx4 v[112:113], v[100:103], off offset:512
	s_nop 1
	v_alignbit_b32 v102, v187, v186, 16
	v_lshlrev_b32_e32 v100, 16, v186
	v_and_b32_e32 v101, 0xffff0000, v186
	v_and_b32_e32 v102, 0xffff0000, v102
	v_and_b32_e32 v103, 0xffff0000, v187
	v_pk_fma_f32 v[92:93], v[92:93], v[128:129], v[100:101]
	v_pk_fma_f32 v[94:95], v[94:95], v[130:131], v[102:103]
	global_store_dwordx4 v[112:113], v[92:95], off offset:576
	v_lshlrev_b64 v[100:101], 12, v[188:189]
	s_nop 0
	v_lshlrev_b32_e32 v92, 16, v196
	v_and_b32_e32 v93, 0xffff0000, v196
	v_alignbit_b32 v94, v197, v196, 16
	v_and_b32_e32 v94, 0xffff0000, v94
	v_and_b32_e32 v95, 0xffff0000, v197
	v_pk_fma_f32 v[92:93], v[96:97], v[140:141], v[92:93]
	v_lshl_add_u64 v[96:97], s[50:51], 0, v[100:101]
	v_pk_fma_f32 v[94:95], v[98:99], v[142:143], v[94:95]
	v_lshl_add_u64 v[96:97], v[96:97], 0, v[156:157]
	global_store_dwordx4 v[96:97], v[92:95], off
	v_add_u32_e32 v98, 0xb0, v160
	v_ashrrev_i32_e32 v99, 31, v98
	v_alignbit_b32 v94, v199, v198, 16
	v_lshlrev_b32_e32 v92, 16, v198
	v_and_b32_e32 v93, 0xffff0000, v198
	v_and_b32_e32 v94, 0xffff0000, v94
	v_and_b32_e32 v95, 0xffff0000, v199
	v_pk_fma_f32 v[88:89], v[88:89], v[136:137], v[92:93]
	v_pk_fma_f32 v[90:91], v[90:91], v[138:139], v[94:95]
	global_store_dwordx4 v[96:97], v[88:91], off offset:64
	s_nop 1
	v_alignbit_b32 v90, v201, v200, 16
	v_lshlrev_b32_e32 v88, 16, v200
	v_and_b32_e32 v89, 0xffff0000, v200
	v_and_b32_e32 v90, 0xffff0000, v90
	v_and_b32_e32 v91, 0xffff0000, v201
	v_pk_fma_f32 v[84:85], v[84:85], v[132:133], v[88:89]
	v_pk_fma_f32 v[86:87], v[86:87], v[134:135], v[90:91]
	global_store_dwordx4 v[96:97], v[84:87], off offset:512
	v_add_u32_e32 v88, 0xa0, v160
	v_ashrrev_i32_e32 v89, 31, v88
	v_alignbit_b32 v86, v193, v192, 16
	v_lshlrev_b32_e32 v84, 16, v192
	v_and_b32_e32 v85, 0xffff0000, v192
	v_and_b32_e32 v86, 0xffff0000, v86
	v_and_b32_e32 v87, 0xffff0000, v193
	v_pk_fma_f32 v[76:77], v[76:77], v[128:129], v[84:85]
	v_pk_fma_f32 v[78:79], v[78:79], v[130:131], v[86:87]
	global_store_dwordx4 v[96:97], v[76:79], off offset:576
	v_lshlrev_b64 v[84:85], 12, v[162:163]
	s_nop 0
	v_lshlrev_b32_e32 v76, 16, v202
	v_and_b32_e32 v77, 0xffff0000, v202
	v_alignbit_b32 v78, v203, v202, 16
	v_and_b32_e32 v78, 0xffff0000, v78
	v_and_b32_e32 v79, 0xffff0000, v203
	v_pk_fma_f32 v[76:77], v[80:81], v[140:141], v[76:77]
	v_lshl_add_u64 v[80:81], s[50:51], 0, v[84:85]
	v_pk_fma_f32 v[78:79], v[82:83], v[142:143], v[78:79]
	v_lshl_add_u64 v[80:81], v[80:81], 0, v[156:157]
	global_store_dwordx4 v[80:81], v[76:79], off
	s_nop 1
	v_alignbit_b32 v78, v205, v204, 16
	v_lshlrev_b32_e32 v76, 16, v204
	v_and_b32_e32 v77, 0xffff0000, v204
	v_and_b32_e32 v78, 0xffff0000, v78
	v_and_b32_e32 v79, 0xffff0000, v205
	v_pk_fma_f32 v[72:73], v[72:73], v[136:137], v[76:77]
	v_pk_fma_f32 v[74:75], v[74:75], v[138:139], v[78:79]
	global_store_dwordx4 v[80:81], v[72:75], off offset:64
	v_add_u32_e32 v78, 0x90, v160
	v_ashrrev_i32_e32 v79, 31, v78
	v_alignbit_b32 v74, v207, v206, 16
	v_lshlrev_b32_e32 v72, 16, v206
	v_and_b32_e32 v73, 0xffff0000, v206
	v_and_b32_e32 v74, 0xffff0000, v74
	v_and_b32_e32 v75, 0xffff0000, v207
	v_pk_fma_f32 v[68:69], v[68:69], v[132:133], v[72:73]
	v_pk_fma_f32 v[70:71], v[70:71], v[134:135], v[74:75]
	global_store_dwordx4 v[80:81], v[68:71], off offset:512
	s_nop 1
	v_lshlrev_b32_e32 v68, 16, v194
	v_and_b32_e32 v69, 0xffff0000, v194
	v_alignbit_b32 v70, v195, v194, 16
	v_and_b32_e32 v70, 0xffff0000, v70
	v_and_b32_e32 v71, 0xffff0000, v195
	v_pk_fma_f32 v[64:65], v[64:65], v[128:129], v[68:69]
	v_add_u32_e32 v68, 0x80, v160
	v_pk_fma_f32 v[66:67], v[66:67], v[130:131], v[70:71]
	v_ashrrev_i32_e32 v69, 31, v68
	global_store_dwordx4 v[80:81], v[64:67], off offset:576
	s_nop 1
	v_lshlrev_b64 v[64:65], 11, v[68:69]
	v_lshl_add_u64 v[64:65], v[158:159], 0, v[64:65]
	v_lshl_add_u64 v[252:253], v[64:65], 0, v[250:251]
	global_load_dwordx4 v[70:73], v[252:253], off nt
	v_lshl_add_u64 v[252:253], v[64:65], 0, v[250:251]
	global_load_dwordx4 v[74:77], v[252:253], off offset:256 nt
	v_lshlrev_b64 v[64:65], 11, v[78:79]
	v_lshl_add_u64 v[64:65], v[158:159], 0, v[64:65]
	v_lshl_add_u64 v[252:253], v[64:65], 0, v[250:251]
	global_load_dwordx4 v[80:83], v[252:253], off nt
	v_lshl_add_u64 v[252:253], v[64:65], 0, v[250:251]
	global_load_dwordx4 v[84:87], v[252:253], off offset:256 nt
	v_lshlrev_b64 v[64:65], 11, v[88:89]
	v_lshl_add_u64 v[64:65], v[158:159], 0, v[64:65]
	v_lshl_add_u64 v[252:253], v[64:65], 0, v[250:251]
	global_load_dwordx4 v[90:93], v[252:253], off nt
	v_lshl_add_u64 v[252:253], v[64:65], 0, v[250:251]
	global_load_dwordx4 v[94:97], v[252:253], off offset:256 nt
	v_lshlrev_b64 v[64:65], 11, v[98:99]
	v_lshl_add_u64 v[64:65], v[158:159], 0, v[64:65]
	v_lshl_add_u64 v[252:253], v[64:65], 0, v[250:251]
	global_load_dwordx4 v[100:103], v[252:253], off nt
	global_load_dwordx2 v[66:67], v[64:65], off offset:256 nt
	s_nop 0
	global_load_dwordx2 v[64:65], v[64:65], off offset:288 nt
	v_lshlrev_b64 v[68:69], 12, v[68:69]
	v_lshl_add_u64 v[68:69], s[50:51], 0, v[68:69]
	v_lshl_add_u64 v[68:69], v[68:69], 0, v[156:157]
	s_waitcnt vmcnt(8)
; __device__ __forceinline__ unsigned cvt_pk_bf16(float lo, float hi) { unsigned r; asm volatile("v_cvt_pk_bf16_f32 %0, %1, %2" : "=v"(r) : "v"(lo), "v"(hi)); return r; }
;     __device__ __forceinline__ void operator()(const f32x4 (&acc)[2][2][4][2], const Unit& u, int wr, int wc, int fr, int fq) const {
;     ...
;             for (int m = 0; m < 4; ++m) { const size_t off = (size_t)(row0 + ai * HALF + m * 16) * 1024 + col0;
; #pragma unroll
;                 for (int bj = 0; bj < 2; ++bj)
; #pragma unroll
;                     for (int n = 0; n < 2; ++n) {
;                         f32x4 b4;
;                         if (BASE_BF16) { const unsigned long long w = bw[m][bj][n];
;                             b4 = (f32x4){__uint_as_float((unsigned)(w & 0xffffull) << 16), __uint_as_float((unsigned)((w >> 16) & 0xffffull) << 16),
;                                          __uint_as_float((unsigned)((w >> 32) & 0xffffull) << 16), __uint_as_float((unsigned)((w >> 48) & 0xffffull) << 16)}; }
;                         else b4 = bv[m][bj][n];
;                         const f32x4 o = b4 + gv[bj][n] * acc[ai][bj][m][n];
;                         if (OUT_BF16) *(unsigned long long*)((bf16_t*)out + off + bj * HALF + 16 * n) = (unsigned long long)cvt_pk_bf16(o[0], o[1]) | ((unsigned long long)cvt_pk_bf16(o[2], o[3]) << 32);
;                         else *(f32x4*)((float*)out + off + bj * HALF + 16 * n) = o; } }
	v_permlane16_swap_b32_e32 v70, v72
	v_permlane16_swap_b32_e32 v71, v73
	s_nop 0
	v_permlane32_swap_b32_e32 v70, v72
	v_permlane32_swap_b32_e32 v71, v73
	s_nop 1
	v_lshlrev_b32_e32 v104, 16, v70
	v_and_b32_e32 v105, 0xffff0000, v70
	v_alignbit_b32 v70, v71, v70, 16
	v_and_b32_e32 v70, 0xffff0000, v70
	v_and_b32_e32 v71, 0xffff0000, v71
	v_pk_fma_f32 v[60:61], v[60:61], v[140:141], v[104:105]
	v_pk_fma_f32 v[62:63], v[62:63], v[142:143], v[70:71]
	global_store_dwordx4 v[68:69], v[60:63], off
	s_waitcnt vmcnt(9)
	s_nop 0
	v_alignbit_b32 v62, v73, v72, 16
	v_lshlrev_b32_e32 v60, 16, v72
	v_and_b32_e32 v61, 0xffff0000, v72
	v_and_b32_e32 v62, 0xffff0000, v62
	v_and_b32_e32 v63, 0xffff0000, v73
	v_pk_fma_f32 v[56:57], v[56:57], v[136:137], v[60:61]
	v_pk_fma_f32 v[58:59], v[58:59], v[138:139], v[62:63]
	global_store_dwordx4 v[68:69], v[56:59], off offset:64
	s_waitcnt vmcnt(9)
	v_permlane16_swap_b32_e32 v74, v76
	v_permlane16_swap_b32_e32 v75, v77
	s_nop 0
	v_permlane32_swap_b32_e32 v74, v76
	v_permlane32_swap_b32_e32 v75, v77
	s_nop 1
	s_nop 0
	v_alignbit_b32 v58, v75, v74, 16
	v_lshlrev_b32_e32 v56, 16, v74
	v_and_b32_e32 v57, 0xffff0000, v74
	v_and_b32_e32 v58, 0xffff0000, v58
	v_and_b32_e32 v59, 0xffff0000, v75
	v_pk_fma_f32 v[52:53], v[52:53], v[132:133], v[56:57]
	v_pk_fma_f32 v[54:55], v[54:55], v[134:135], v[58:59]
	global_store_dwordx4 v[68:69], v[52:55], off offset:512
	s_waitcnt vmcnt(10)
	s_nop 0
	v_alignbit_b32 v54, v77, v76, 16
	v_lshlrev_b32_e32 v52, 16, v76
	v_and_b32_e32 v53, 0xffff0000, v76
	v_and_b32_e32 v54, 0xffff0000, v54
	v_and_b32_e32 v55, 0xffff0000, v77
	v_pk_fma_f32 v[44:45], v[44:45], v[128:129], v[52:53]
	v_pk_fma_f32 v[46:47], v[46:47], v[130:131], v[54:55]
	global_store_dwordx4 v[68:69], v[44:47], off offset:576
	v_lshlrev_b64 v[52:53], 12, v[78:79]
	s_waitcnt vmcnt(10)
	v_permlane16_swap_b32_e32 v80, v82
	v_permlane16_swap_b32_e32 v81, v83
	s_nop 0
	v_permlane32_swap_b32_e32 v80, v82
	v_permlane32_swap_b32_e32 v81, v83
	s_nop 1
	v_lshlrev_b32_e32 v44, 16, v80
	v_and_b32_e32 v45, 0xffff0000, v80
	v_alignbit_b32 v46, v81, v80, 16
	v_and_b32_e32 v46, 0xffff0000, v46
	v_and_b32_e32 v47, 0xffff0000, v81
	v_pk_fma_f32 v[44:45], v[48:49], v[140:141], v[44:45]
	v_lshl_add_u64 v[48:49], s[50:51], 0, v[52:53]
	v_pk_fma_f32 v[46:47], v[50:51], v[142:143], v[46:47]
	v_lshl_add_u64 v[48:49], v[48:49], 0, v[156:157]
	global_store_dwordx4 v[48:49], v[44:47], off
	s_waitcnt vmcnt(11)
	s_nop 0
	v_alignbit_b32 v46, v83, v82, 16
	v_lshlrev_b32_e32 v44, 16, v82
	v_and_b32_e32 v45, 0xffff0000, v82
	v_and_b32_e32 v46, 0xffff0000, v46
	v_and_b32_e32 v47, 0xffff0000, v83
	v_pk_fma_f32 v[40:41], v[40:41], v[136:137], v[44:45]
	v_pk_fma_f32 v[42:43], v[42:43], v[138:139], v[46:47]
	global_store_dwordx4 v[48:49], v[40:43], off offset:64
	s_waitcnt vmcnt(11)
	v_permlane16_swap_b32_e32 v84, v86
	v_permlane16_swap_b32_e32 v85, v87
	s_nop 0
	v_permlane32_swap_b32_e32 v84, v86
	v_permlane32_swap_b32_e32 v85, v87
	s_nop 1
	s_nop 0
	v_alignbit_b32 v42, v85, v84, 16
	v_lshlrev_b32_e32 v40, 16, v84
	v_and_b32_e32 v41, 0xffff0000, v84
	v_and_b32_e32 v42, 0xffff0000, v42
	v_and_b32_e32 v43, 0xffff0000, v85
	v_pk_fma_f32 v[36:37], v[36:37], v[132:133], v[40:41]
	v_pk_fma_f32 v[38:39], v[38:39], v[134:135], v[42:43]
	global_store_dwordx4 v[48:49], v[36:39], off offset:512
	s_waitcnt vmcnt(12)
	s_nop 0
	v_alignbit_b32 v38, v87, v86, 16
	v_lshlrev_b32_e32 v36, 16, v86
	v_and_b32_e32 v37, 0xffff0000, v86
	v_and_b32_e32 v38, 0xffff0000, v38
	v_and_b32_e32 v39, 0xffff0000, v87
	v_pk_fma_f32 v[28:29], v[28:29], v[128:129], v[36:37]
	v_pk_fma_f32 v[30:31], v[30:31], v[130:131], v[38:39]
	global_store_dwordx4 v[48:49], v[28:31], off offset:576
	v_lshlrev_b64 v[36:37], 12, v[88:89]
	s_waitcnt vmcnt(12)
; __device__ __forceinline__ unsigned cvt_pk_bf16(float lo, float hi) { unsigned r; asm volatile("v_cvt_pk_bf16_f32 %0, %1, %2" : "=v"(r) : "v"(lo), "v"(hi)); return r; }
;     __device__ __forceinline__ void operator()(const f32x4 (&acc)[2][2][4][2], const Unit& u, int wr, int wc, int fr, int fq) const {
;     ...
;             for (int m = 0; m < 4; ++m) { const size_t off = (size_t)(row0 + ai * HALF + m * 16) * 1024 + col0;
; #pragma unroll
;                 for (int bj = 0; bj < 2; ++bj)
; #pragma unroll
;                     for (int n = 0; n < 2; ++n) {
;                         f32x4 b4;
;                         if (BASE_BF16) { const unsigned long long w = bw[m][bj][n];
;                             b4 = (f32x4){__uint_as_float((unsigned)(w & 0xffffull) << 16), __uint_as_float((unsigned)((w >> 16) & 0xffffull) << 16),
;                                          __uint_as_float((unsigned)((w >> 32) & 0xffffull) << 16), __uint_as_float((unsigned)((w >> 48) & 0xffffull) << 16)}; }
;                         else b4 = bv[m][bj][n];
;                         const f32x4 o = b4 + gv[bj][n] * acc[ai][bj][m][n];
;                         if (OUT_BF16) *(unsigned long long*)((bf16_t*)out + off + bj * HALF + 16 * n) = (unsigned long long)cvt_pk_bf16(o[0], o[1]) | ((unsigned long long)cvt_pk_bf16(o[2], o[3]) << 32);
;                         else *(f32x4*)((float*)out + off + bj * HALF + 16 * n) = o; } }
	v_permlane16_swap_b32_e32 v90, v92
	v_permlane16_swap_b32_e32 v91, v93
	s_nop 0
	v_permlane32_swap_b32_e32 v90, v92
	v_permlane32_swap_b32_e32 v91, v93
	s_nop 1
	v_lshlrev_b32_e32 v28, 16, v90
	v_and_b32_e32 v29, 0xffff0000, v90
	v_alignbit_b32 v30, v91, v90, 16
	v_and_b32_e32 v30, 0xffff0000, v30
	v_and_b32_e32 v31, 0xffff0000, v91
	v_pk_fma_f32 v[28:29], v[32:33], v[140:141], v[28:29]
	v_lshl_add_u64 v[32:33], s[50:51], 0, v[36:37]
	v_pk_fma_f32 v[30:31], v[34:35], v[142:143], v[30:31]
	v_lshl_add_u64 v[32:33], v[32:33], 0, v[156:157]
	global_store_dwordx4 v[32:33], v[28:31], off
	s_waitcnt vmcnt(13)
	s_nop 0
	v_alignbit_b32 v30, v93, v92, 16
	v_lshlrev_b32_e32 v28, 16, v92
	v_and_b32_e32 v29, 0xffff0000, v92
	v_and_b32_e32 v30, 0xffff0000, v30
	v_and_b32_e32 v31, 0xffff0000, v93
	v_pk_fma_f32 v[24:25], v[24:25], v[136:137], v[28:29]
	v_pk_fma_f32 v[26:27], v[26:27], v[138:139], v[30:31]
	global_store_dwordx4 v[32:33], v[24:27], off offset:64
	s_waitcnt vmcnt(13)
	v_permlane16_swap_b32_e32 v94, v96
	v_permlane16_swap_b32_e32 v95, v97
	s_nop 0
	v_permlane32_swap_b32_e32 v94, v96
	v_permlane32_swap_b32_e32 v95, v97
	s_nop 1
	s_nop 0
	v_alignbit_b32 v26, v95, v94, 16
	v_lshlrev_b32_e32 v24, 16, v94
	v_and_b32_e32 v25, 0xffff0000, v94
	v_and_b32_e32 v26, 0xffff0000, v26
	v_and_b32_e32 v27, 0xffff0000, v95
	v_pk_fma_f32 v[20:21], v[20:21], v[132:133], v[24:25]
	v_pk_fma_f32 v[22:23], v[22:23], v[134:135], v[26:27]
	global_store_dwordx4 v[32:33], v[20:23], off offset:512
	s_waitcnt vmcnt(14)
	s_nop 0
	v_alignbit_b32 v22, v97, v96, 16
	v_lshlrev_b32_e32 v20, 16, v96
	v_and_b32_e32 v21, 0xffff0000, v96
	v_and_b32_e32 v22, 0xffff0000, v22
	v_and_b32_e32 v23, 0xffff0000, v97
	v_pk_fma_f32 v[12:13], v[12:13], v[128:129], v[20:21]
	v_pk_fma_f32 v[14:15], v[14:15], v[130:131], v[22:23]
	global_store_dwordx4 v[32:33], v[12:15], off offset:576
	v_lshlrev_b64 v[20:21], 12, v[98:99]
	s_waitcnt vmcnt(14)
	v_permlane16_swap_b32_e32 v100, v102
	v_permlane16_swap_b32_e32 v101, v103
	s_nop 0
	v_permlane32_swap_b32_e32 v100, v102
	v_permlane32_swap_b32_e32 v101, v103
	s_nop 1
	v_lshlrev_b32_e32 v12, 16, v100
	v_and_b32_e32 v13, 0xffff0000, v100
	v_alignbit_b32 v14, v101, v100, 16
	v_and_b32_e32 v14, 0xffff0000, v14
	v_and_b32_e32 v15, 0xffff0000, v101
	v_pk_fma_f32 v[12:13], v[16:17], v[140:141], v[12:13]
	v_lshl_add_u64 v[16:17], s[50:51], 0, v[20:21]
	v_pk_fma_f32 v[14:15], v[18:19], v[142:143], v[14:15]
	v_lshl_add_u64 v[16:17], v[16:17], 0, v[156:157]
	global_store_dwordx4 v[16:17], v[12:15], off
	s_waitcnt vmcnt(15)
	s_nop 0
	v_alignbit_b32 v14, v103, v102, 16
	v_lshlrev_b32_e32 v12, 16, v102
	v_and_b32_e32 v13, 0xffff0000, v102
	v_and_b32_e32 v14, 0xffff0000, v14
	v_and_b32_e32 v15, 0xffff0000, v103
	v_pk_fma_f32 v[8:9], v[8:9], v[136:137], v[12:13]
	v_pk_fma_f32 v[10:11], v[10:11], v[138:139], v[14:15]
	global_store_dwordx4 v[16:17], v[8:11], off offset:64
	s_waitcnt vmcnt(15)
	s_nop 0
	v_alignbit_b32 v10, v67, v66, 16
	v_lshlrev_b32_e32 v8, 16, v66
	v_and_b32_e32 v9, 0xffff0000, v66
	v_and_b32_e32 v10, 0xffff0000, v10
	v_and_b32_e32 v11, 0xffff0000, v67
	v_pk_fma_f32 v[4:5], v[4:5], v[132:133], v[8:9]
	v_pk_fma_f32 v[6:7], v[6:7], v[134:135], v[10:11]
	global_store_dwordx4 v[16:17], v[4:7], off offset:512
	s_waitcnt vmcnt(15)
	s_nop 0
	v_alignbit_b32 v6, v65, v64, 16
	v_lshlrev_b32_e32 v4, 16, v64
	v_and_b32_e32 v5, 0xffff0000, v64
	v_and_b32_e32 v6, 0xffff0000, v6
	v_and_b32_e32 v7, 0xffff0000, v65
	v_pk_fma_f32 v[0:1], v[0:1], v[128:129], v[4:5]
	v_pk_fma_f32 v[2:3], v[2:3], v[130:131], v[6:7]
	global_store_dwordx4 v[16:17], v[0:3], off offset:576
	s_cbranch_vccnz .LBB0_1468
	s_andn2_b64 vcc, exec, s[6:7]
	s_cbranch_vccnz .LBB0_1467
	s_barrier
	s_branch .LBB0_1467
